# v47 + gated-conv unit: 7 of the 8 per-row gate loads prefetched at unit start (were serialized load-wait-use per row); per-row waits removed
# speedup vs baseline: 1.0075x; 1.0075x over previous
.LBB0_127:
	v_mov_b32_e32 v26, v243
	s_load_dwordx2 s[6:7], s[58:59], 0x38
	v_lshlrev_b32_e32 v0, 3, v26
	v_and_b32_e32 v28, 0x1f8, v0
	v_lshlrev_b32_e32 v0, 2, v28
	s_mov_b64 s[8:9], 0x1000
	s_waitcnt lgkmcnt(0)
	s_add_u32 s6, s6, s10
	s_addc_u32 s7, s7, s1
	v_lshl_add_u64 v[18:19], s[6:7], 0, v[0:1]
	v_lshl_add_u64 v[20:21], v[18:19], 0, s[8:9]
	global_load_dwordx4 v[2:5], v0, s[6:7] offset:16
	global_load_dwordx4 v[6:9], v0, s[6:7]
	global_load_dwordx4 v[10:13], v0, s[6:7] offset:2064
	global_load_dwordx4 v[14:17], v0, s[6:7] offset:2048
	v_add_co_u32_e32 v18, vcc, s75, v18
	v_ashrrev_i32_e32 v0, 3, v26
	s_nop 0
	v_addc_co_u32_e32 v19, vcc, 0, v19, vcc
	global_load_dwordx4 v[22:25], v[18:19], off
	s_nop 0
	global_load_dwordx4 v[18:21], v[20:21], off offset:16
	v_and_b32_e32 v0, -8, v0
	v_add_u32_e32 v26, s11, v0
	s_movk_i32 s6, 0xff8
	v_add_u32_e32 v27, -2, v26
	v_and_or_b32 v60, v26, s6, 7
	v_and_b32_e32 v0, 0xffe, v27
	v_cmp_lt_i32_e32 vcc, 1, v26
	v_cmp_le_u32_e64 s[38:39], v0, v60
	s_and_b64 s[8:9], vcc, s[38:39]
	v_mov_b32_e32 v40, 0
	v_lshlrev_b32_e32 v0, 1, v28
	v_mov_b32_e32 v56, 0
	v_mov_b32_e32 v57, 0
	v_mov_b32_e32 v48, 0
	v_mov_b32_e32 v49, 0
	v_mov_b32_e32 v42, 0
	v_mov_b32_e32 v43, 0
	v_mov_b32_e32 v36, 0
	v_mov_b32_e32 v37, 0
	v_lshl_add_u64 v[66:67], s[2:3], 0, v[0:1]
	v_mad_i64_i32 v[68:69], s[38:39], v26, s47, v[66:67]
	global_load_dwordx4 v[70:73], v[68:69], off
	v_add_u32_e32 v65, 1, v26
	v_mad_i64_i32 v[68:69], s[38:39], v65, s47, v[66:67]
	global_load_dwordx4 v[74:77], v[68:69], off
	v_add_u32_e32 v65, 2, v26
	v_mad_i64_i32 v[68:69], s[38:39], v65, s47, v[66:67]
	global_load_dwordx4 v[78:81], v[68:69], off
	v_add_u32_e32 v65, 3, v26
	v_mad_i64_i32 v[68:69], s[38:39], v65, s47, v[66:67]
	global_load_dwordx4 v[82:85], v[68:69], off
	v_add_u32_e32 v65, 4, v26
	v_mad_i64_i32 v[68:69], s[38:39], v65, s47, v[66:67]
	global_load_dwordx4 v[86:89], v[68:69], off
	v_add_u32_e32 v65, 5, v26
	v_mad_i64_i32 v[68:69], s[38:39], v65, s47, v[66:67]
	global_load_dwordx4 v[90:93], v[68:69], off
	v_add_u32_e32 v65, 6, v26
	v_mad_i64_i32 v[68:69], s[38:39], v65, s47, v[66:67]
	global_load_dwordx4 v[94:97], v[68:69], off
	s_and_saveexec_b64 s[6:7], s[8:9]
	s_cbranch_execz .LBB0_129
	v_mov_b64_e32 v[28:29], s[2:3]
	v_mad_u64_u32 v[28:29], s[8:9], v27, s47, v[28:29]
	v_lshl_add_u64 v[32:33], v[28:29], 0, v[0:1]
	global_load_dwordx4 v[28:31], v[32:33], off offset:1024
	s_nop 0
	global_load_dwordx4 v[32:35], v[32:33], off offset:2048
	s_waitcnt vmcnt(1)
	v_lshlrev_b32_e32 v38, 16, v28
	v_and_b32_e32 v39, 0xffff0000, v28
	s_waitcnt vmcnt(0)
	v_lshlrev_b32_e32 v44, 16, v32
	v_and_b32_e32 v45, 0xffff0000, v32
	v_lshlrev_b32_e32 v28, 16, v29
	v_and_b32_e32 v29, 0xffff0000, v29
	v_lshlrev_b32_e32 v32, 16, v33
	v_and_b32_e32 v33, 0xffff0000, v33
	v_lshlrev_b32_e32 v42, 16, v30
	v_and_b32_e32 v43, 0xffff0000, v30
	v_lshlrev_b32_e32 v46, 16, v34
	v_and_b32_e32 v47, 0xffff0000, v34
	v_lshlrev_b32_e32 v30, 16, v31
	v_lshlrev_b32_e32 v34, 16, v35
	v_and_b32_e32 v35, 0xffff0000, v35
	v_and_b32_e32 v31, 0xffff0000, v31
	v_pk_mul_f32 v[36:37], v[30:31], v[34:35]
	v_pk_mul_f32 v[48:49], v[28:29], v[32:33]
	v_pk_mul_f32 v[42:43], v[42:43], v[46:47]
	v_pk_mul_f32 v[56:57], v[38:39], v[44:45]

.LBB0_133:
	s_or_b64 exec, exec, s[6:7]
	v_lshl_add_u64 v[30:31], s[2:3], 0, v[0:1]
	v_mad_i64_i32 v[58:59], s[6:7], v26, s47, v[30:31]
	s_waitcnt vmcnt(0)
	v_mov_b32_e32 v62, v70
	v_mov_b32_e32 v63, v71
	v_mov_b32_e32 v64, v72
	v_mov_b32_e32 v65, v73
	v_pk_mul_f32 v[58:59], v[22:23], v[52:53]
	v_ashrrev_i32_e32 v27, 31, v26
	v_pk_fma_f32 v[58:59], v[14:15], v[40:41], v[58:59]
	v_lshl_add_u64 v[28:29], s[4:5], 0, v[0:1]
	v_pk_fma_f32 v[56:57], v[6:7], v[56:57], v[58:59]
	v_mov_b32_e32 v33, 0
	s_waitcnt vmcnt(0)
	v_lshlrev_b32_e32 v58, 16, v62
	v_and_b32_e32 v59, 0xffff0000, v62
	v_pk_mul_f32 v[56:57], v[56:57], v[58:59]
	v_pk_mul_f32 v[58:59], v[24:25], v[50:51]
	v_cvt_pk_bf16_f32 v56, v56, v57
	v_pk_fma_f32 v[58:59], v[16:17], v[54:55], v[58:59]
	s_nop 0
	v_pk_fma_f32 v[48:49], v[8:9], v[48:49], v[58:59]
	v_lshlrev_b32_e32 v58, 16, v63
	v_and_b32_e32 v59, 0xffff0000, v63
	v_pk_mul_f32 v[48:49], v[48:49], v[58:59]
	s_nop 0
	v_cvt_pk_bf16_f32 v57, v48, v49
	v_pk_mul_f32 v[48:49], v[18:19], v[44:45]
	s_nop 0
	v_pk_fma_f32 v[48:49], v[10:11], v[46:47], v[48:49]
	s_nop 0
	v_pk_fma_f32 v[42:43], v[2:3], v[42:43], v[48:49]
	v_lshlrev_b32_e32 v48, 16, v64
	v_and_b32_e32 v49, 0xffff0000, v64
	v_pk_mul_f32 v[42:43], v[42:43], v[48:49]
	v_mov_b32_e32 v48, 0
	v_cvt_pk_bf16_f32 v58, v42, v43
	v_pk_mul_f32 v[42:43], v[20:21], v[38:39]
	v_mov_b32_e32 v49, 0
	v_pk_fma_f32 v[42:43], v[12:13], v[34:35], v[42:43]
	s_nop 0
	v_pk_fma_f32 v[36:37], v[4:5], v[36:37], v[42:43]
	v_lshlrev_b32_e32 v42, 16, v65
	v_and_b32_e32 v43, 0xffff0000, v65
	v_pk_mul_f32 v[36:37], v[36:37], v[42:43]
	v_mov_b32_e32 v42, 0
	v_cvt_pk_bf16_f32 v59, v36, v37
	v_lshlrev_b64 v[36:37], 11, v[26:27]
	v_lshl_add_u64 v[36:37], v[28:29], 0, v[36:37]
	global_store_dwordx4 v[36:37], v[56:59], off
	v_mov_b32_e32 v43, 0
	v_mov_b32_e32 v36, 0
	v_add_u32_e32 v56, 1, v26
	v_and_b32_e32 v27, 0xff9, v56
	v_cmp_le_u32_e64 s[38:39], v27, v60
	s_and_b64 s[6:7], vcc, s[38:39]
	v_mov_b32_e32 v37, 0
	s_and_saveexec_b64 s[8:9], s[6:7]
	s_cbranch_execz .LBB0_135
	v_mov_b64_e32 v[32:33], s[2:3]
	v_mad_u64_u32 v[32:33], s[6:7], v56, s47, v[32:33]
	v_lshl_add_u64 v[32:33], v[32:33], 0, v[0:1]
	global_load_dwordx4 v[62:65], v[32:33], off offset:1024
	global_load_dwordx4 v[66:69], v[32:33], off offset:2048
	s_waitcnt vmcnt(1)
	v_lshlrev_b32_e32 v32, 16, v62
	v_and_b32_e32 v33, 0xffff0000, v62
	s_waitcnt vmcnt(0)
	v_lshlrev_b32_e32 v58, 16, v66
	v_and_b32_e32 v59, 0xffff0000, v66
	v_lshlrev_b32_e32 v42, 16, v63
	v_and_b32_e32 v43, 0xffff0000, v63
	v_lshlrev_b32_e32 v48, 16, v67
	v_and_b32_e32 v49, 0xffff0000, v67
	v_lshlrev_b32_e32 v62, 16, v64
	v_and_b32_e32 v63, 0xffff0000, v64
	v_lshlrev_b32_e32 v66, 16, v68
	v_and_b32_e32 v67, 0xffff0000, v68
	v_lshlrev_b32_e32 v36, 16, v65
	v_lshlrev_b32_e32 v68, 16, v69
	v_and_b32_e32 v69, 0xffff0000, v69
	v_and_b32_e32 v37, 0xffff0000, v65
	v_pk_mul_f32 v[36:37], v[36:37], v[68:69]
	v_pk_mul_f32 v[48:49], v[42:43], v[48:49]
	v_pk_mul_f32 v[42:43], v[62:63], v[66:67]
	v_pk_mul_f32 v[32:33], v[32:33], v[58:59]
.LBB0_135:
	s_or_b64 exec, exec, s[8:9]
	v_mad_i64_i32 v[58:59], s[6:7], v56, s47, v[30:31]
	v_mov_b32_e32 v62, v74
	v_mov_b32_e32 v63, v75
	v_mov_b32_e32 v64, v76
	v_mov_b32_e32 v65, v77
	v_pk_mul_f32 v[58:59], v[22:23], v[32:33]
	v_ashrrev_i32_e32 v57, 31, v56
	v_pk_fma_f32 v[58:59], v[14:15], v[52:53], v[58:59]
	s_nop 0
	v_pk_fma_f32 v[40:41], v[6:7], v[40:41], v[58:59]
	v_lshlrev_b32_e32 v58, 16, v62
	v_and_b32_e32 v59, 0xffff0000, v62
	v_pk_mul_f32 v[40:41], v[40:41], v[58:59]
	v_mov_b32_e32 v58, 0
	v_cvt_pk_bf16_f32 v62, v40, v41
	v_pk_mul_f32 v[40:41], v[24:25], v[48:49]
	v_mov_b32_e32 v59, 0
	v_pk_fma_f32 v[40:41], v[16:17], v[50:51], v[40:41]
	s_nop 0
	v_pk_fma_f32 v[40:41], v[8:9], v[54:55], v[40:41]
	v_lshlrev_b32_e32 v54, 16, v63
	v_and_b32_e32 v55, 0xffff0000, v63
	v_pk_mul_f32 v[40:41], v[40:41], v[54:55]
	v_mov_b32_e32 v54, 0
	v_cvt_pk_bf16_f32 v63, v40, v41
	v_pk_mul_f32 v[40:41], v[18:19], v[42:43]
	v_mov_b32_e32 v55, 0
	v_pk_fma_f32 v[40:41], v[10:11], v[44:45], v[40:41]
	s_nop 0
	v_pk_fma_f32 v[40:41], v[2:3], v[46:47], v[40:41]
	v_lshlrev_b32_e32 v46, 16, v64
	v_and_b32_e32 v47, 0xffff0000, v64
	v_pk_mul_f32 v[40:41], v[40:41], v[46:47]
	v_mov_b32_e32 v46, 0
	v_cvt_pk_bf16_f32 v64, v40, v41
	v_pk_mul_f32 v[40:41], v[20:21], v[36:37]
	v_mov_b32_e32 v47, 0
	v_pk_fma_f32 v[40:41], v[12:13], v[38:39], v[40:41]
	s_nop 0
	v_pk_fma_f32 v[34:35], v[4:5], v[34:35], v[40:41]
	v_lshlrev_b32_e32 v40, 16, v65
	v_and_b32_e32 v41, 0xffff0000, v65
	v_pk_mul_f32 v[34:35], v[34:35], v[40:41]
	v_mov_b32_e32 v40, 0
	v_cvt_pk_bf16_f32 v65, v34, v35
	v_lshlrev_b64 v[34:35], 11, v[56:57]
	v_add_u32_e32 v56, 2, v26
	v_and_b32_e32 v27, 0xffa, v56
	v_lshl_add_u64 v[34:35], v[28:29], 0, v[34:35]
	v_cmp_le_u32_e64 s[38:39], v27, v60
	global_store_dwordx4 v[34:35], v[62:65], off
	s_and_b64 s[6:7], vcc, s[38:39]
	v_mov_b32_e32 v34, 0
	v_mov_b32_e32 v41, 0
	s_and_saveexec_b64 s[8:9], s[6:7]
	s_cbranch_execz .LBB0_137
	v_mov_b64_e32 v[40:41], s[2:3]
	v_mad_u64_u32 v[40:41], s[6:7], v56, s47, v[40:41]
	v_lshl_add_u64 v[40:41], v[40:41], 0, v[0:1]
	global_load_dwordx4 v[62:65], v[40:41], off offset:1024
	global_load_dwordx4 v[66:69], v[40:41], off offset:2048
	s_waitcnt vmcnt(1)
	v_lshlrev_b32_e32 v58, 16, v62
	v_and_b32_e32 v59, 0xffff0000, v62
	s_waitcnt vmcnt(0)
	v_lshlrev_b32_e32 v70, 16, v66
	v_and_b32_e32 v71, 0xffff0000, v66
	v_lshlrev_b32_e32 v46, 16, v63
	v_and_b32_e32 v47, 0xffff0000, v63
	v_lshlrev_b32_e32 v54, 16, v67
	v_and_b32_e32 v55, 0xffff0000, v67
	v_lshlrev_b32_e32 v62, 16, v64
	v_and_b32_e32 v63, 0xffff0000, v64
	v_lshlrev_b32_e32 v66, 16, v68
	v_and_b32_e32 v67, 0xffff0000, v68
	v_lshlrev_b32_e32 v40, 16, v65
	v_lshlrev_b32_e32 v68, 16, v69
	v_and_b32_e32 v69, 0xffff0000, v69
	v_and_b32_e32 v41, 0xffff0000, v65
	v_pk_mul_f32 v[40:41], v[40:41], v[68:69]
	v_pk_mul_f32 v[54:55], v[46:47], v[54:55]
	v_pk_mul_f32 v[46:47], v[62:63], v[66:67]
	v_pk_mul_f32 v[58:59], v[58:59], v[70:71]
.LBB0_137:
	s_or_b64 exec, exec, s[8:9]
	v_mad_i64_i32 v[62:63], s[6:7], v56, s47, v[30:31]
	v_mov_b32_e32 v62, v78
	v_mov_b32_e32 v63, v79
	v_mov_b32_e32 v64, v80
	v_mov_b32_e32 v65, v81
	v_pk_mul_f32 v[66:67], v[22:23], v[58:59]
	v_ashrrev_i32_e32 v57, 31, v56
	v_pk_fma_f32 v[66:67], v[14:15], v[32:33], v[66:67]
	v_mov_b32_e32 v35, 0
	v_pk_fma_f32 v[52:53], v[6:7], v[52:53], v[66:67]
	v_lshlrev_b32_e32 v66, 16, v62
	v_and_b32_e32 v67, 0xffff0000, v62
	v_pk_mul_f32 v[52:53], v[52:53], v[66:67]
	s_nop 0
	v_cvt_pk_bf16_f32 v62, v52, v53
	v_pk_mul_f32 v[52:53], v[24:25], v[54:55]
	s_nop 0
	v_pk_fma_f32 v[52:53], v[16:17], v[48:49], v[52:53]
	s_nop 0
	v_pk_fma_f32 v[50:51], v[8:9], v[50:51], v[52:53]
	v_lshlrev_b32_e32 v52, 16, v63
	v_and_b32_e32 v53, 0xffff0000, v63
	v_pk_mul_f32 v[50:51], v[50:51], v[52:53]
	v_mov_b32_e32 v52, 0
	v_cvt_pk_bf16_f32 v63, v50, v51
	v_pk_mul_f32 v[50:51], v[18:19], v[46:47]
	v_mov_b32_e32 v53, 0
	v_pk_fma_f32 v[50:51], v[10:11], v[42:43], v[50:51]
	s_nop 0
	v_pk_fma_f32 v[44:45], v[2:3], v[44:45], v[50:51]
	v_lshlrev_b32_e32 v50, 16, v64
	v_and_b32_e32 v51, 0xffff0000, v64
	v_pk_mul_f32 v[44:45], v[44:45], v[50:51]
	v_add_u32_e32 v50, 3, v26
	v_cvt_pk_bf16_f32 v64, v44, v45
	v_pk_mul_f32 v[44:45], v[20:21], v[40:41]
	v_and_b32_e32 v27, 0xffb, v50
	v_pk_fma_f32 v[44:45], v[12:13], v[36:37], v[44:45]
	v_cmp_le_u32_e64 s[38:39], v27, v60
	v_pk_fma_f32 v[38:39], v[4:5], v[38:39], v[44:45]
	v_lshlrev_b32_e32 v44, 16, v65
	v_and_b32_e32 v45, 0xffff0000, v65
	v_pk_mul_f32 v[38:39], v[38:39], v[44:45]
	s_and_b64 s[6:7], vcc, s[38:39]
	v_cvt_pk_bf16_f32 v65, v38, v39
	v_lshlrev_b64 v[38:39], 11, v[56:57]
	v_lshl_add_u64 v[38:39], v[28:29], 0, v[38:39]
	global_store_dwordx4 v[38:39], v[62:65], off
	v_mov_b32_e32 v44, 0
	v_mov_b32_e32 v45, 0
	v_mov_b32_e32 v38, 0
	v_mov_b32_e32 v39, 0
	s_and_saveexec_b64 s[8:9], s[6:7]
	s_cbranch_execz .LBB0_139
	v_mov_b64_e32 v[34:35], s[2:3]
	v_mad_u64_u32 v[34:35], s[6:7], v50, s47, v[34:35]
	v_lshl_add_u64 v[34:35], v[34:35], 0, v[0:1]
	global_load_dwordx4 v[62:65], v[34:35], off offset:1024
	global_load_dwordx4 v[66:69], v[34:35], off offset:2048
	s_waitcnt vmcnt(1)
	v_lshlrev_b32_e32 v34, 16, v62
	v_and_b32_e32 v35, 0xffff0000, v62
	s_waitcnt vmcnt(0)
	v_lshlrev_b32_e32 v56, 16, v66
	v_and_b32_e32 v57, 0xffff0000, v66
	v_lshlrev_b32_e32 v44, 16, v63
	v_and_b32_e32 v45, 0xffff0000, v63
	v_lshlrev_b32_e32 v52, 16, v67
	v_and_b32_e32 v53, 0xffff0000, v67
	v_lshlrev_b32_e32 v62, 16, v64
	v_and_b32_e32 v63, 0xffff0000, v64
	v_lshlrev_b32_e32 v66, 16, v68
	v_and_b32_e32 v67, 0xffff0000, v68
	v_lshlrev_b32_e32 v38, 16, v65
	v_lshlrev_b32_e32 v68, 16, v69
	v_and_b32_e32 v69, 0xffff0000, v69
	v_and_b32_e32 v39, 0xffff0000, v65
	v_pk_mul_f32 v[38:39], v[38:39], v[68:69]
	v_pk_mul_f32 v[52:53], v[44:45], v[52:53]
	v_pk_mul_f32 v[44:45], v[62:63], v[66:67]
	v_pk_mul_f32 v[34:35], v[34:35], v[56:57]
.LBB0_139:
	s_or_b64 exec, exec, s[8:9]
	v_mad_i64_i32 v[56:57], s[6:7], v50, s47, v[30:31]
	v_mov_b32_e32 v62, v82
	v_mov_b32_e32 v63, v83
	v_mov_b32_e32 v64, v84
	v_mov_b32_e32 v65, v85
	v_pk_mul_f32 v[56:57], v[22:23], v[34:35]
	v_ashrrev_i32_e32 v51, 31, v50
	v_pk_fma_f32 v[56:57], v[14:15], v[58:59], v[56:57]
	s_nop 0
	v_pk_fma_f32 v[32:33], v[6:7], v[32:33], v[56:57]
	v_lshlrev_b32_e32 v56, 16, v62
	v_and_b32_e32 v57, 0xffff0000, v62
	v_pk_mul_f32 v[32:33], v[32:33], v[56:57]
	v_mov_b32_e32 v56, 0
	v_cvt_pk_bf16_f32 v62, v32, v33
	v_pk_mul_f32 v[32:33], v[24:25], v[52:53]
	v_mov_b32_e32 v57, 0
	v_pk_fma_f32 v[32:33], v[16:17], v[54:55], v[32:33]
	s_nop 0
	v_pk_fma_f32 v[32:33], v[8:9], v[48:49], v[32:33]
	v_lshlrev_b32_e32 v48, 16, v63
	v_and_b32_e32 v49, 0xffff0000, v63
	v_pk_mul_f32 v[32:33], v[32:33], v[48:49]
	v_add_u32_e32 v48, 4, v26
	v_cvt_pk_bf16_f32 v63, v32, v33
	v_pk_mul_f32 v[32:33], v[18:19], v[44:45]
	v_and_b32_e32 v27, 0xffc, v48
	v_pk_fma_f32 v[32:33], v[10:11], v[46:47], v[32:33]
	v_cmp_le_u32_e64 s[38:39], v27, v60
	v_pk_fma_f32 v[32:33], v[2:3], v[42:43], v[32:33]
	v_lshlrev_b32_e32 v42, 16, v64
	v_and_b32_e32 v43, 0xffff0000, v64
	v_pk_mul_f32 v[32:33], v[32:33], v[42:43]
	s_and_b64 s[6:7], vcc, s[38:39]
	v_cvt_pk_bf16_f32 v64, v32, v33
	v_pk_mul_f32 v[32:33], v[20:21], v[38:39]
	v_mov_b32_e32 v42, 0
	v_pk_fma_f32 v[32:33], v[12:13], v[40:41], v[32:33]
	v_mov_b32_e32 v43, 0
	v_pk_fma_f32 v[32:33], v[4:5], v[36:37], v[32:33]
	v_lshlrev_b32_e32 v36, 16, v65
	v_and_b32_e32 v37, 0xffff0000, v65
	v_pk_mul_f32 v[32:33], v[32:33], v[36:37]
	v_mov_b32_e32 v36, 0
	v_cvt_pk_bf16_f32 v65, v32, v33
	v_lshlrev_b64 v[32:33], 11, v[50:51]
	v_lshl_add_u64 v[32:33], v[28:29], 0, v[32:33]
	global_store_dwordx4 v[32:33], v[62:65], off
	v_mov_b32_e32 v32, 0
	v_mov_b32_e32 v50, 0
	v_mov_b32_e32 v51, 0
	v_mov_b32_e32 v37, 0
	s_and_saveexec_b64 s[8:9], s[6:7]
	s_cbranch_execz .LBB0_141
	v_mov_b64_e32 v[36:37], s[2:3]
	v_mad_u64_u32 v[36:37], s[6:7], v48, s47, v[36:37]
	v_lshl_add_u64 v[36:37], v[36:37], 0, v[0:1]
	global_load_dwordx4 v[62:65], v[36:37], off offset:1024
	global_load_dwordx4 v[66:69], v[36:37], off offset:2048
	s_waitcnt vmcnt(1)
	v_lshlrev_b32_e32 v56, 16, v62
	v_and_b32_e32 v57, 0xffff0000, v62
	s_waitcnt vmcnt(0)
	v_lshlrev_b32_e32 v70, 16, v66
	v_and_b32_e32 v71, 0xffff0000, v66
	v_lshlrev_b32_e32 v42, 16, v63
	v_and_b32_e32 v43, 0xffff0000, v63
	v_lshlrev_b32_e32 v50, 16, v67
	v_and_b32_e32 v51, 0xffff0000, v67
	v_lshlrev_b32_e32 v62, 16, v64
	v_and_b32_e32 v63, 0xffff0000, v64
	v_lshlrev_b32_e32 v66, 16, v68
	v_and_b32_e32 v67, 0xffff0000, v68
	v_lshlrev_b32_e32 v36, 16, v65
	v_lshlrev_b32_e32 v68, 16, v69
	v_and_b32_e32 v69, 0xffff0000, v69
	v_and_b32_e32 v37, 0xffff0000, v65
	v_pk_mul_f32 v[36:37], v[36:37], v[68:69]
	v_pk_mul_f32 v[50:51], v[42:43], v[50:51]
	v_pk_mul_f32 v[42:43], v[62:63], v[66:67]
	v_pk_mul_f32 v[56:57], v[56:57], v[70:71]
.LBB0_141:
	s_or_b64 exec, exec, s[8:9]
	v_mad_i64_i32 v[62:63], s[6:7], v48, s47, v[30:31]
	v_mov_b32_e32 v62, v86
	v_mov_b32_e32 v63, v87
	v_mov_b32_e32 v64, v88
	v_mov_b32_e32 v65, v89
	v_pk_mul_f32 v[66:67], v[22:23], v[56:57]
	v_ashrrev_i32_e32 v49, 31, v48
	v_pk_fma_f32 v[66:67], v[14:15], v[34:35], v[66:67]
	v_mov_b32_e32 v33, 0
	v_pk_fma_f32 v[58:59], v[6:7], v[58:59], v[66:67]
	v_lshlrev_b32_e32 v66, 16, v62
	v_and_b32_e32 v67, 0xffff0000, v62
	v_pk_mul_f32 v[58:59], v[58:59], v[66:67]
	s_nop 0
	v_cvt_pk_bf16_f32 v62, v58, v59
	v_pk_mul_f32 v[58:59], v[24:25], v[50:51]
	s_nop 0
	v_pk_fma_f32 v[58:59], v[16:17], v[52:53], v[58:59]
	s_nop 0
	v_pk_fma_f32 v[54:55], v[8:9], v[54:55], v[58:59]
	v_lshlrev_b32_e32 v58, 16, v63
	v_and_b32_e32 v59, 0xffff0000, v63
	v_pk_mul_f32 v[54:55], v[54:55], v[58:59]
	s_nop 0
	v_cvt_pk_bf16_f32 v63, v54, v55
	v_pk_mul_f32 v[54:55], v[18:19], v[42:43]
	s_nop 0
	v_pk_fma_f32 v[54:55], v[10:11], v[44:45], v[54:55]
	s_nop 0
	v_pk_fma_f32 v[46:47], v[2:3], v[46:47], v[54:55]
	v_lshlrev_b32_e32 v54, 16, v64
	v_and_b32_e32 v55, 0xffff0000, v64
	v_pk_mul_f32 v[46:47], v[46:47], v[54:55]
	v_add_u32_e32 v54, 5, v26
	v_cvt_pk_bf16_f32 v64, v46, v47
	v_pk_mul_f32 v[46:47], v[20:21], v[36:37]
	v_and_b32_e32 v27, 0xffd, v54
	v_pk_fma_f32 v[46:47], v[12:13], v[38:39], v[46:47]
	v_cmp_le_u32_e64 s[38:39], v27, v60
	v_pk_fma_f32 v[40:41], v[4:5], v[40:41], v[46:47]
	v_lshlrev_b32_e32 v46, 16, v65
	v_and_b32_e32 v47, 0xffff0000, v65
	v_pk_mul_f32 v[40:41], v[40:41], v[46:47]
	s_and_b64 s[6:7], vcc, s[38:39]
	v_cvt_pk_bf16_f32 v65, v40, v41
	v_lshlrev_b64 v[40:41], 11, v[48:49]
	v_lshl_add_u64 v[40:41], v[28:29], 0, v[40:41]
	global_store_dwordx4 v[40:41], v[62:65], off
	v_mov_b32_e32 v46, 0
	v_mov_b32_e32 v47, 0
	v_mov_b32_e32 v48, 0
	v_mov_b32_e32 v49, 0
	v_mov_b32_e32 v40, 0
	v_mov_b32_e32 v41, 0
	s_and_saveexec_b64 s[8:9], s[6:7]
	s_cbranch_execz .LBB0_143
	v_mov_b64_e32 v[32:33], s[2:3]
	v_mad_u64_u32 v[32:33], s[6:7], v54, s47, v[32:33]
	v_lshl_add_u64 v[32:33], v[32:33], 0, v[0:1]
	global_load_dwordx4 v[46:49], v[32:33], off offset:1024
	global_load_dwordx4 v[62:65], v[32:33], off offset:2048
	s_waitcnt vmcnt(1)
	v_lshlrev_b32_e32 v32, 16, v46
	v_and_b32_e32 v33, 0xffff0000, v46
	s_waitcnt vmcnt(0)
	v_lshlrev_b32_e32 v58, 16, v62
	v_and_b32_e32 v59, 0xffff0000, v62
	v_lshlrev_b32_e32 v46, 16, v47
	v_and_b32_e32 v47, 0xffff0000, v47
	v_lshlrev_b32_e32 v62, 16, v63
	v_and_b32_e32 v63, 0xffff0000, v63
	v_lshlrev_b32_e32 v66, 16, v48
	v_and_b32_e32 v67, 0xffff0000, v48
	v_lshlrev_b32_e32 v68, 16, v64
	v_and_b32_e32 v69, 0xffff0000, v64
	v_lshlrev_b32_e32 v40, 16, v49
	v_lshlrev_b32_e32 v64, 16, v65
	v_and_b32_e32 v65, 0xffff0000, v65
	v_and_b32_e32 v41, 0xffff0000, v49
	v_pk_mul_f32 v[40:41], v[40:41], v[64:65]
	v_pk_mul_f32 v[46:47], v[46:47], v[62:63]
	v_pk_mul_f32 v[48:49], v[66:67], v[68:69]
	v_pk_mul_f32 v[32:33], v[32:33], v[58:59]
.LBB0_143:
	s_or_b64 exec, exec, s[8:9]
	v_mad_i64_i32 v[58:59], s[6:7], v54, s47, v[30:31]
	v_mov_b32_e32 v62, v90
	v_mov_b32_e32 v63, v91
	v_mov_b32_e32 v64, v92
	v_mov_b32_e32 v65, v93
	v_pk_mul_f32 v[58:59], v[22:23], v[32:33]
	v_ashrrev_i32_e32 v55, 31, v54
	v_pk_fma_f32 v[58:59], v[14:15], v[56:57], v[58:59]
	s_nop 0
	v_pk_fma_f32 v[34:35], v[6:7], v[34:35], v[58:59]
	v_lshlrev_b32_e32 v58, 16, v62
	v_and_b32_e32 v59, 0xffff0000, v62
	v_pk_mul_f32 v[34:35], v[34:35], v[58:59]
	v_add_u32_e32 v58, 6, v26
	v_cvt_pk_bf16_f32 v62, v34, v35
	v_pk_mul_f32 v[34:35], v[24:25], v[46:47]
	v_and_b32_e32 v27, 0xffe, v58
	v_pk_fma_f32 v[34:35], v[16:17], v[50:51], v[34:35]
	v_cmp_le_u32_e64 s[38:39], v27, v60
	v_pk_fma_f32 v[34:35], v[8:9], v[52:53], v[34:35]
	v_lshlrev_b32_e32 v52, 16, v63
	v_and_b32_e32 v53, 0xffff0000, v63
	v_pk_mul_f32 v[34:35], v[34:35], v[52:53]
	s_and_b64 s[6:7], vcc, s[38:39]
	v_cvt_pk_bf16_f32 v63, v34, v35
	v_pk_mul_f32 v[34:35], v[18:19], v[48:49]
	v_mov_b32_e32 v52, 0
	v_pk_fma_f32 v[34:35], v[10:11], v[42:43], v[34:35]
	v_mov_b32_e32 v53, 0
	v_pk_fma_f32 v[34:35], v[2:3], v[44:45], v[34:35]
	v_lshlrev_b32_e32 v44, 16, v64
	v_and_b32_e32 v45, 0xffff0000, v64
	v_pk_mul_f32 v[34:35], v[34:35], v[44:45]
	v_mov_b32_e32 v44, 0
	v_cvt_pk_bf16_f32 v64, v34, v35
	v_pk_mul_f32 v[34:35], v[20:21], v[40:41]
	v_mov_b32_e32 v45, 0
	v_pk_fma_f32 v[34:35], v[12:13], v[36:37], v[34:35]
	s_nop 0
	v_pk_fma_f32 v[34:35], v[4:5], v[38:39], v[34:35]
	v_lshlrev_b32_e32 v38, 16, v65
	v_and_b32_e32 v39, 0xffff0000, v65
	v_pk_mul_f32 v[34:35], v[34:35], v[38:39]
	v_mov_b32_e32 v38, 0
	v_cvt_pk_bf16_f32 v65, v34, v35
	v_lshlrev_b64 v[34:35], 11, v[54:55]
	v_lshl_add_u64 v[34:35], v[28:29], 0, v[34:35]
	global_store_dwordx4 v[34:35], v[62:65], off
	v_mov_b32_e32 v54, 0
	v_mov_b32_e32 v39, 0
	v_mov_b32_e32 v34, 0
	v_mov_b32_e32 v35, 0
	s_and_saveexec_b64 s[8:9], s[6:7]
	s_cbranch_execz .LBB0_145
	v_mov_b64_e32 v[34:35], s[2:3]
	v_mad_u64_u32 v[34:35], s[6:7], v58, s47, v[34:35]
	v_lshl_add_u64 v[34:35], v[34:35], 0, v[0:1]
	global_load_dwordx4 v[62:65], v[34:35], off offset:1024
	global_load_dwordx4 v[66:69], v[34:35], off offset:2048
	s_waitcnt vmcnt(1)
	v_lshlrev_b32_e32 v52, 16, v62
	v_and_b32_e32 v53, 0xffff0000, v62
	s_waitcnt vmcnt(0)
	v_lshlrev_b32_e32 v70, 16, v66
	v_and_b32_e32 v71, 0xffff0000, v66
	v_lshlrev_b32_e32 v38, 16, v63
	v_and_b32_e32 v39, 0xffff0000, v63
	v_lshlrev_b32_e32 v44, 16, v67
	v_and_b32_e32 v45, 0xffff0000, v67
	v_lshlrev_b32_e32 v62, 16, v64
	v_and_b32_e32 v63, 0xffff0000, v64
	v_lshlrev_b32_e32 v66, 16, v68
	v_and_b32_e32 v67, 0xffff0000, v68
	v_lshlrev_b32_e32 v34, 16, v65
	v_lshlrev_b32_e32 v68, 16, v69
	v_and_b32_e32 v69, 0xffff0000, v69
	v_and_b32_e32 v35, 0xffff0000, v65
	v_pk_mul_f32 v[34:35], v[34:35], v[68:69]
	v_pk_mul_f32 v[38:39], v[38:39], v[44:45]
	v_pk_mul_f32 v[44:45], v[62:63], v[66:67]
	v_pk_mul_f32 v[52:53], v[52:53], v[70:71]
.LBB0_145:
	s_or_b64 exec, exec, s[8:9]
	v_mad_i64_i32 v[62:63], s[6:7], v58, s47, v[30:31]
	v_mov_b32_e32 v62, v94
	v_mov_b32_e32 v63, v95
	v_mov_b32_e32 v64, v96
	v_mov_b32_e32 v65, v97
	v_pk_mul_f32 v[66:67], v[22:23], v[52:53]
	v_ashrrev_i32_e32 v59, 31, v58
	v_pk_fma_f32 v[66:67], v[14:15], v[32:33], v[66:67]
	v_add_u32_e32 v26, 7, v26
	v_pk_fma_f32 v[56:57], v[6:7], v[56:57], v[66:67]
	v_and_b32_e32 v27, 0xfff, v26
	v_cmp_le_u32_e64 s[38:39], v27, v60
	s_and_b64 s[6:7], vcc, s[38:39]
	v_mov_b32_e32 v55, 0
	v_lshlrev_b32_e32 v66, 16, v62
	v_and_b32_e32 v67, 0xffff0000, v62
	v_pk_mul_f32 v[56:57], v[56:57], v[66:67]
	s_nop 0
	v_cvt_pk_bf16_f32 v62, v56, v57
	v_pk_mul_f32 v[56:57], v[24:25], v[38:39]
	s_nop 0
	v_pk_fma_f32 v[56:57], v[16:17], v[46:47], v[56:57]
	s_nop 0
	v_pk_fma_f32 v[50:51], v[8:9], v[50:51], v[56:57]
	v_lshlrev_b32_e32 v56, 16, v63
	v_and_b32_e32 v57, 0xffff0000, v63
	v_pk_mul_f32 v[50:51], v[50:51], v[56:57]
	s_nop 0
	v_cvt_pk_bf16_f32 v63, v50, v51
	v_pk_mul_f32 v[50:51], v[18:19], v[44:45]
	s_nop 0
	v_pk_fma_f32 v[50:51], v[10:11], v[48:49], v[50:51]
	s_nop 0
	v_pk_fma_f32 v[42:43], v[2:3], v[42:43], v[50:51]
	v_lshlrev_b32_e32 v50, 16, v64
	v_and_b32_e32 v51, 0xffff0000, v64
	v_pk_mul_f32 v[42:43], v[42:43], v[50:51]
	v_mov_b32_e32 v50, 0
	v_cvt_pk_bf16_f32 v64, v42, v43
	v_pk_mul_f32 v[42:43], v[20:21], v[34:35]
	v_mov_b32_e32 v51, 0
	v_pk_fma_f32 v[42:43], v[12:13], v[40:41], v[42:43]
	s_nop 0
	v_pk_fma_f32 v[36:37], v[4:5], v[36:37], v[42:43]
	v_lshlrev_b32_e32 v42, 16, v65
	v_and_b32_e32 v43, 0xffff0000, v65
	v_pk_mul_f32 v[36:37], v[36:37], v[42:43]
	v_mov_b32_e32 v42, 0
	v_cvt_pk_bf16_f32 v65, v36, v37
	v_lshlrev_b64 v[36:37], 11, v[58:59]
	v_lshl_add_u64 v[36:37], v[28:29], 0, v[36:37]
	global_store_dwordx4 v[36:37], v[62:65], off
	v_mov_b32_e32 v43, 0
	v_mov_b32_e32 v36, 0
	v_mov_b32_e32 v37, 0
	s_and_saveexec_b64 s[8:9], s[6:7]
	s_cbranch_execz .LBB0_126
	v_mov_b64_e32 v[36:37], s[2:3]
	v_mad_u64_u32 v[36:37], s[6:7], v26, s47, v[36:37]
	v_lshl_add_u64 v[36:37], v[36:37], 0, v[0:1]
	global_load_dwordx4 v[54:57], v[36:37], off offset:1024
	global_load_dwordx4 v[58:61], v[36:37], off offset:2048
	s_waitcnt vmcnt(1)
	v_lshlrev_b32_e32 v62, 16, v54
	v_and_b32_e32 v63, 0xffff0000, v54
	s_waitcnt vmcnt(0)
	v_lshlrev_b32_e32 v64, 16, v58
	v_and_b32_e32 v65, 0xffff0000, v58
	v_lshlrev_b32_e32 v42, 16, v55
	v_and_b32_e32 v43, 0xffff0000, v55
	v_lshlrev_b32_e32 v50, 16, v59
	v_and_b32_e32 v51, 0xffff0000, v59
	v_lshlrev_b32_e32 v54, 16, v56
	v_and_b32_e32 v55, 0xffff0000, v56
	v_lshlrev_b32_e32 v58, 16, v60
	v_and_b32_e32 v59, 0xffff0000, v60
	v_lshlrev_b32_e32 v36, 16, v57
	v_lshlrev_b32_e32 v60, 16, v61
	v_and_b32_e32 v61, 0xffff0000, v61
	v_and_b32_e32 v37, 0xffff0000, v57
	v_pk_mul_f32 v[36:37], v[36:37], v[60:61]
	v_pk_mul_f32 v[50:51], v[42:43], v[50:51]
	v_pk_mul_f32 v[42:43], v[54:55], v[58:59]
	v_pk_mul_f32 v[54:55], v[62:63], v[64:65]
	s_branch .LBB0_126
